# speedup vs baseline: 1.0132x; 1.0017x over previous
; __device__ __forceinline__ void phase_ln(const float* __restrict__ pre, const float* __restrict__ g, const float* __restrict__ bta,
;                          float* __restrict__ outf, u16* __restrict__ outb) {
;     ...
;   for (int row = bid * (blockDim.x >> 6) + w; row < NTOK; row += nw) {
;     const f32x4* src = reinterpret_cast<const f32x4*>(pre + (long)row * D);
;     f32x4 v[16];
;     float s = 0.f;
; #pragma unroll
;     for (int i = 0; i < 16; ++i) { v[i] = src[i * 64 + l]; s += v[i][0] + v[i][1] + v[i][2] + v[i][3]; }
; #pragma unroll
;     for (int o = 32; o >= 1; o >>= 1) s += __shfl_xor(s, o);
;     const float mu = s * (1.0f / D);
;     float q = 0.f;
; #pragma unroll
;     for (int i = 0; i < 16; ++i)
; #pragma unroll
;       for (int e = 0; e < 4; ++e) { float d = v[i][e] - mu; q += d * d; }
; #pragma unroll
;     for (int o = 32; o >= 1; o >>= 1) q += __shfl_xor(q, o);
;     const float rstd = rsqrtf(q * (1.0f / D) + LN_EPS);
.LBB0_1273:
	v_lshl_add_u64 v[50:51], v[116:117], 0, v[0:1]
	s_mov_b32 s0, 0x30c11000
	v_add_co_u32_e32 v10, vcc, s0, v50
	s_mov_b32 s0, 0x30c12000
	s_nop 0
	v_addc_co_u32_e32 v11, vcc, 0, v51, vcc
	global_load_dwordx4 v[58:61], v[10:11], off
	global_load_dwordx4 v[54:57], v[10:11], off offset:1024
	global_load_dwordx4 v[18:21], v[10:11], off offset:2048
	global_load_dwordx4 v[14:17], v[10:11], off offset:3072
	v_add_co_u32_e32 v10, vcc, s0, v50
	s_mov_b32 s0, 0x30c13000
	s_nop 0
	v_addc_co_u32_e32 v11, vcc, 0, v51, vcc
	global_load_dwordx4 v[38:41], v[10:11], off
	global_load_dwordx4 v[34:37], v[10:11], off offset:1024
	global_load_dwordx4 v[26:29], v[10:11], off offset:2048
	global_load_dwordx4 v[22:25], v[10:11], off offset:3072
	v_add_co_u32_e32 v10, vcc, s0, v50
	s_nop 1
	v_addc_co_u32_e32 v11, vcc, 0, v51, vcc
	global_load_dwordx4 v[46:49], v[10:11], off
	global_load_dwordx4 v[42:45], v[10:11], off offset:1024
	global_load_dwordx4 v[30:33], v[10:11], off offset:2048
	s_nop 0
	global_load_dwordx4 v[10:13], v[10:11], off offset:3072
	v_add_co_u32_e32 v130, vcc, 0x30c10000, v50
	s_nop 0
	v_addc_co_u32_e32 v131, vcc, 0, v51, vcc
	global_load_dwordx4 v[50:53], v[130:131], off
	global_load_dwordx4 v[122:125], v[130:131], off offset:1024
	global_load_dwordx4 v[126:129], v[130:131], off offset:2048
	global_load_dwordx4 v[136:139], v[130:131], off offset:3072
	s_waitcnt vmcnt(8)
	v_add_f32_e32 v63, v58, v59
	v_add_f32_e32 v150, v54, v55
	v_add_f32_e32 v63, v60, v63
	v_add_f32_e32 v151, v18, v19
	v_add_f32_e32 v150, v56, v150
	v_add_f32_e32 v63, v61, v63
	v_add_f32_e32 v152, v14, v15
	v_add_f32_e32 v151, v20, v151
	v_add_f32_e32 v150, v57, v150
	v_add_f32_e32 v153, v38, v39
	v_add_f32_e32 v152, v16, v152
	v_add_f32_e32 v151, v21, v151
	v_add_f32_e32 v154, v34, v35
	v_add_f32_e32 v153, v40, v153
	v_add_f32_e32 v152, v17, v152
	v_add_f32_e32 v155, v26, v27
	v_add_f32_e32 v154, v36, v154
	v_add_f32_e32 v153, v41, v153
	v_add_f32_e32 v156, v22, v23
	v_add_f32_e32 v155, v28, v155
	v_add_f32_e32 v154, v37, v154
	v_add_f32_e32 v156, v24, v156
	v_add_f32_e32 v155, v29, v155
	v_add_f32_e32 v156, v25, v156
	s_waitcnt vmcnt(0) lgkmcnt(0)
	v_mov_b32_e32 v130, v46
	v_mov_b32_e32 v131, v42
	v_mov_b32_e32 v140, v47
	v_mov_b32_e32 v141, v43
	v_mov_b32_e32 v146, v30
	v_mov_b32_e32 v147, v10
	v_mov_b32_e32 v148, v31
	v_mov_b32_e32 v149, v11
	v_add_f32_e32 v157, v50, v51
	v_mov_b32_e32 v142, v48
	v_mov_b32_e32 v143, v44
	v_add_f32_e32 v163, v122, v123
	v_pk_add_f32 v[130:131], v[130:131], v[140:141]
	v_pk_add_f32 v[140:141], v[146:147], v[148:149]
	v_add_f32_e32 v146, v52, v157
	v_add_f32_e32 v164, v126, v127
	v_add_f32_e32 v147, v124, v163
	v_pk_add_f32 v[130:131], v[142:143], v[130:131]
	v_add_f32_e32 v142, v53, v146
	v_add_f32_e32 v165, v136, v137
	v_add_f32_e32 v148, v128, v164
	v_add_f32_e32 v143, v125, v147
	v_add_f32_e32 v142, 0, v142
	v_add_f32_e32 v149, v138, v165
	v_add_f32_e32 v146, v129, v148
	v_add_f32_e32 v142, v142, v143
	v_add_f32_e32 v147, v139, v149
	v_add_f32_e32 v142, v142, v146
	v_add_f32_e32 v142, v142, v147
	v_add_f32_e32 v63, v142, v63
	v_add_f32_e32 v63, v63, v150
	v_add_f32_e32 v63, v63, v151
	v_add_f32_e32 v63, v63, v152
	v_add_f32_e32 v63, v63, v153
	v_add_f32_e32 v63, v63, v154
	v_mov_b32_e32 v144, v49
	v_mov_b32_e32 v145, v45
	v_add_f32_e32 v63, v63, v155
	v_pk_add_f32 v[130:131], v[144:145], v[130:131]
	v_add_f32_e32 v63, v63, v156
	v_add_f32_e32 v63, v63, v130
	v_add_f32_e32 v63, v63, v131
	v_mov_b32_e32 v130, v32
	v_mov_b32_e32 v131, v12
	v_pk_add_f32 v[130:131], v[130:131], v[140:141]
	v_mov_b32_e32 v140, v33
	v_mov_b32_e32 v141, v13
	v_pk_add_f32 v[130:131], v[140:141], v[130:131]
	s_nop 0
	v_add_f32_e32 v63, v63, v130
	v_add_f32_e32 v63, v63, v131
	ds_bpermute_b32 v130, v135, v63
	s_waitcnt lgkmcnt(0)
	v_add_f32_e32 v63, v63, v130
	ds_bpermute_b32 v130, v158, v63
	s_waitcnt lgkmcnt(0)
	v_add_f32_e32 v63, v63, v130
	ds_bpermute_b32 v130, v159, v63
	s_waitcnt lgkmcnt(0)
	v_add_f32_e32 v63, v63, v130
	ds_bpermute_b32 v130, v160, v63
	s_waitcnt lgkmcnt(0)
	v_add_f32_e32 v63, v63, v130
	ds_bpermute_b32 v130, v161, v63
	s_waitcnt lgkmcnt(0)
	v_add_f32_e32 v63, v63, v130
	ds_bpermute_b32 v130, v162, v63
	s_waitcnt lgkmcnt(0)
	v_add_f32_e32 v63, v63, v130
	v_mul_f32_e32 v164, 0x39800000, v63
	v_pk_add_f32 v[50:51], v[50:51], v[164:165] op_sel_hi:[1,0] neg_lo:[0,1] neg_hi:[0,1]
	v_pk_add_f32 v[52:53], v[52:53], v[164:165] op_sel_hi:[1,0] neg_lo:[0,1] neg_hi:[0,1]
	v_pk_mul_f32 v[222:223], v[50:51], v[50:51]
	v_pk_add_f32 v[154:155], v[122:123], v[164:165] op_sel_hi:[1,0] neg_lo:[0,1] neg_hi:[0,1]
	v_pk_add_f32 v[156:157], v[124:125], v[164:165] op_sel_hi:[1,0] neg_lo:[0,1] neg_hi:[0,1]
	v_pk_add_f32 v[150:151], v[126:127], v[164:165] op_sel_hi:[1,0] neg_lo:[0,1] neg_hi:[0,1]
	v_pk_add_f32 v[152:153], v[128:129], v[164:165] op_sel_hi:[1,0] neg_lo:[0,1] neg_hi:[0,1]
	v_pk_add_f32 v[146:147], v[136:137], v[164:165] op_sel_hi:[1,0] neg_lo:[0,1] neg_hi:[0,1]
	v_pk_add_f32 v[148:149], v[138:139], v[164:165] op_sel_hi:[1,0] neg_lo:[0,1] neg_hi:[0,1]
	v_pk_add_f32 v[142:143], v[58:59], v[164:165] op_sel_hi:[1,0] neg_lo:[0,1] neg_hi:[0,1]
	v_pk_add_f32 v[144:145], v[60:61], v[164:165] op_sel_hi:[1,0] neg_lo:[0,1] neg_hi:[0,1]
	v_pk_add_f32 v[138:139], v[54:55], v[164:165] op_sel_hi:[1,0] neg_lo:[0,1] neg_hi:[0,1]
	v_pk_add_f32 v[140:141], v[56:57], v[164:165] op_sel_hi:[1,0] neg_lo:[0,1] neg_hi:[0,1]
	v_pk_add_f32 v[130:131], v[18:19], v[164:165] op_sel_hi:[1,0] neg_lo:[0,1] neg_hi:[0,1]
	v_pk_add_f32 v[136:137], v[20:21], v[164:165] op_sel_hi:[1,0] neg_lo:[0,1] neg_hi:[0,1]
	v_pk_add_f32 v[126:127], v[14:15], v[164:165] op_sel_hi:[1,0] neg_lo:[0,1] neg_hi:[0,1]
; __device__ __forceinline__ void phase_ln(const float* __restrict__ pre, const float* __restrict__ g, const float* __restrict__ bta,
;                          float* __restrict__ outf, u16* __restrict__ outb) {
;     ...
;     float q = 0.f;
; #pragma unroll
;     for (int i = 0; i < 16; ++i)
; #pragma unroll
;       for (int e = 0; e < 4; ++e) { float d = v[i][e] - mu; q += d * d; }
; #pragma unroll
;     for (int o = 32; o >= 1; o >>= 1) q += __shfl_xor(q, o);
;     const float rstd = rsqrtf(q * (1.0f / D) + LN_EPS);
; #pragma unroll
;     for (int i = 0; i < 16; ++i) {
;       const int col4 = i * 64 + l;
;       f32x4 gg = reinterpret_cast<const f32x4*>(g)[col4], bb = reinterpret_cast<const f32x4*>(bta)[col4];
;       f32x4 y;
; #pragma unroll
;       for (int e = 0; e < 4; ++e) y[e] = (v[i][e] - mu) * rstd * gg[e] + bb[e];
;       if (outf) __builtin_nontemporal_store(y, reinterpret_cast<f32x4*>(outf + (long)row * D) + col4);
;       if (outb) reinterpret_cast<u32x2*>(outb + (long)row * D)[col4] = u32x2{pk2(y[0], y[1]), pk2(y[2], y[3])};
;     }
	v_pk_add_f32 v[128:129], v[16:17], v[164:165] op_sel_hi:[1,0] neg_lo:[0,1] neg_hi:[0,1]
	v_pk_add_f32 v[122:123], v[38:39], v[164:165] op_sel_hi:[1,0] neg_lo:[0,1] neg_hi:[0,1]
	v_pk_add_f32 v[124:125], v[40:41], v[164:165] op_sel_hi:[1,0] neg_lo:[0,1] neg_hi:[0,1]
	v_pk_add_f32 v[58:59], v[34:35], v[164:165] op_sel_hi:[1,0] neg_lo:[0,1] neg_hi:[0,1]
	v_pk_add_f32 v[60:61], v[36:37], v[164:165] op_sel_hi:[1,0] neg_lo:[0,1] neg_hi:[0,1]
	v_pk_add_f32 v[54:55], v[26:27], v[164:165] op_sel_hi:[1,0] neg_lo:[0,1] neg_hi:[0,1]
	v_pk_add_f32 v[56:57], v[28:29], v[164:165] op_sel_hi:[1,0] neg_lo:[0,1] neg_hi:[0,1]
	v_pk_add_f32 v[38:39], v[22:23], v[164:165] op_sel_hi:[1,0] neg_lo:[0,1] neg_hi:[0,1]
	v_pk_add_f32 v[40:41], v[24:25], v[164:165] op_sel_hi:[1,0] neg_lo:[0,1] neg_hi:[0,1]
	v_pk_add_f32 v[34:35], v[46:47], v[164:165] op_sel_hi:[1,0] neg_lo:[0,1] neg_hi:[0,1]
	v_pk_add_f32 v[36:37], v[48:49], v[164:165] op_sel_hi:[1,0] neg_lo:[0,1] neg_hi:[0,1]
	v_pk_add_f32 v[24:25], v[42:43], v[164:165] op_sel_hi:[1,0] neg_lo:[0,1] neg_hi:[0,1]
	v_pk_add_f32 v[26:27], v[44:45], v[164:165] op_sel_hi:[1,0] neg_lo:[0,1] neg_hi:[0,1]
	v_pk_add_f32 v[18:19], v[30:31], v[164:165] op_sel_hi:[1,0] neg_lo:[0,1] neg_hi:[0,1]
	v_pk_add_f32 v[20:21], v[32:33], v[164:165] op_sel_hi:[1,0] neg_lo:[0,1] neg_hi:[0,1]
	v_pk_add_f32 v[14:15], v[10:11], v[164:165] op_sel_hi:[1,0] neg_lo:[0,1] neg_hi:[0,1]
	v_pk_add_f32 v[16:17], v[12:13], v[164:165] op_sel_hi:[1,0] neg_lo:[0,1] neg_hi:[0,1]
	v_pk_mul_f32 v[164:165], v[52:53], v[52:53]
	v_add_f32_e32 v63, v222, v223
	v_add_f32_e32 v63, v164, v63
	v_pk_mul_f32 v[182:183], v[154:155], v[154:155]
	v_add_f32_e32 v63, v165, v63
	v_add_f32_e32 v63, v182, v63
	v_pk_mul_f32 v[184:185], v[156:157], v[156:157]
	v_add_f32_e32 v63, v183, v63
	v_add_f32_e32 v63, v184, v63
	v_pk_mul_f32 v[186:187], v[150:151], v[150:151]
	v_add_f32_e32 v63, v185, v63
	v_add_f32_e32 v63, v186, v63
	v_pk_mul_f32 v[188:189], v[152:153], v[152:153]
	v_add_f32_e32 v63, v187, v63
	v_add_f32_e32 v63, v188, v63
	v_pk_mul_f32 v[190:191], v[146:147], v[146:147]
	v_add_f32_e32 v63, v189, v63
	v_add_f32_e32 v63, v190, v63
	v_pk_mul_f32 v[192:193], v[148:149], v[148:149]
	v_add_f32_e32 v63, v191, v63
	v_add_f32_e32 v63, v192, v63
	v_pk_mul_f32 v[194:195], v[142:143], v[142:143]
	v_add_f32_e32 v63, v193, v63
	v_add_f32_e32 v63, v194, v63
	v_pk_mul_f32 v[196:197], v[144:145], v[144:145]
	v_add_f32_e32 v63, v195, v63
	v_add_f32_e32 v63, v196, v63
	v_pk_mul_f32 v[198:199], v[138:139], v[138:139]
	v_add_f32_e32 v63, v197, v63
	v_add_f32_e32 v63, v198, v63
	v_pk_mul_f32 v[200:201], v[140:141], v[140:141]
	v_add_f32_e32 v63, v199, v63
	v_add_f32_e32 v63, v200, v63
	v_pk_mul_f32 v[202:203], v[130:131], v[130:131]
	v_add_f32_e32 v63, v201, v63
	v_add_f32_e32 v63, v202, v63
	v_pk_mul_f32 v[204:205], v[136:137], v[136:137]
	v_add_f32_e32 v63, v203, v63
	v_add_f32_e32 v63, v204, v63
	v_pk_mul_f32 v[206:207], v[126:127], v[126:127]
	v_add_f32_e32 v63, v205, v63
	v_add_f32_e32 v63, v206, v63
	v_pk_mul_f32 v[208:209], v[128:129], v[128:129]
	v_add_f32_e32 v63, v207, v63
	v_add_f32_e32 v63, v208, v63
	v_pk_mul_f32 v[210:211], v[122:123], v[122:123]
	v_add_f32_e32 v63, v209, v63
	v_add_f32_e32 v63, v210, v63
	v_pk_mul_f32 v[212:213], v[124:125], v[124:125]
	v_add_f32_e32 v63, v211, v63
	v_add_f32_e32 v63, v212, v63
	v_pk_mul_f32 v[214:215], v[58:59], v[58:59]
	v_add_f32_e32 v63, v213, v63
	v_add_f32_e32 v63, v214, v63
	v_pk_mul_f32 v[216:217], v[60:61], v[60:61]
	v_add_f32_e32 v63, v215, v63
	v_add_f32_e32 v63, v216, v63
	v_pk_mul_f32 v[218:219], v[54:55], v[54:55]
	v_add_f32_e32 v63, v217, v63
	v_add_f32_e32 v63, v218, v63
	v_pk_mul_f32 v[28:29], v[56:57], v[56:57]
	v_add_f32_e32 v63, v219, v63
	v_add_f32_e32 v28, v28, v63
	v_pk_mul_f32 v[22:23], v[38:39], v[38:39]
	v_add_f32_e32 v28, v29, v28
	v_add_f32_e32 v22, v22, v28
	v_pk_mul_f32 v[220:221], v[40:41], v[40:41]
	v_add_f32_e32 v22, v23, v22
	v_add_f32_e32 v22, v220, v22
	v_pk_mul_f32 v[46:47], v[34:35], v[34:35]
	v_add_f32_e32 v22, v221, v22
	v_add_f32_e32 v22, v46, v22
	v_pk_mul_f32 v[48:49], v[36:37], v[36:37]
	v_add_f32_e32 v22, v47, v22
	v_add_f32_e32 v22, v48, v22
	v_pk_mul_f32 v[42:43], v[24:25], v[24:25]
	v_add_f32_e32 v22, v49, v22
	v_add_f32_e32 v22, v42, v22
	v_pk_mul_f32 v[44:45], v[26:27], v[26:27]
	v_add_f32_e32 v22, v43, v22
	v_add_f32_e32 v22, v44, v22
	v_pk_mul_f32 v[30:31], v[18:19], v[18:19]
	v_add_f32_e32 v22, v45, v22
	v_add_f32_e32 v22, v30, v22
	v_pk_mul_f32 v[32:33], v[20:21], v[20:21]
	v_add_f32_e32 v22, v31, v22
	v_add_f32_e32 v22, v32, v22
	v_pk_mul_f32 v[10:11], v[14:15], v[14:15]
	v_add_f32_e32 v22, v33, v22
	v_add_f32_e32 v10, v10, v22
	v_pk_mul_f32 v[12:13], v[16:17], v[16:17]
	v_add_f32_e32 v10, v11, v10
	v_add_f32_e32 v10, v12, v10
	v_add_f32_e32 v10, v13, v10
	ds_bpermute_b32 v11, v135, v10
	v_cndmask_b32_e64 v22, 0, 1, s[14:15]
	v_cmp_ne_u32_e64 s[6:7], 1, v22
	v_lshl_add_u64 v[22:23], v[118:119], 0, v[0:1]
	s_waitcnt lgkmcnt(0)
	v_add_f32_e32 v10, v10, v11
	ds_bpermute_b32 v11, v158, v10
	s_waitcnt lgkmcnt(0)
	v_add_f32_e32 v10, v10, v11
	ds_bpermute_b32 v11, v159, v10
	s_waitcnt lgkmcnt(0)
	v_add_f32_e32 v10, v10, v11
	ds_bpermute_b32 v11, v160, v10
	s_waitcnt lgkmcnt(0)
	v_add_f32_e32 v10, v10, v11
	ds_bpermute_b32 v11, v161, v10
	s_waitcnt lgkmcnt(0)
	v_add_f32_e32 v10, v10, v11
	ds_bpermute_b32 v11, v162, v10
	s_waitcnt lgkmcnt(0)
	v_add_f32_e32 v10, v10, v11
	v_fmamk_f32 v10, v10, 0x39800000, v167
	v_mul_f32_e32 v11, 0x4b800000, v10
	v_cmp_gt_f32_e32 vcc, s16, v10
	s_nop 1
	v_cndmask_b32_e32 v10, v10, v11, vcc
	v_rsq_f32_e32 v10, v10
	s_nop 0
	v_mul_f32_e32 v11, 0x45800000, v10
	v_cndmask_b32_e32 v28, v10, v11, vcc
	v_pk_mul_f32 v[10:11], v[50:51], v[28:29] op_sel_hi:[1,0]
	v_pk_mul_f32 v[12:13], v[52:53], v[28:29] op_sel_hi:[1,0]
	v_pk_fma_f32 v[10:11], v[2:3], v[10:11], v[6:7]
	v_pk_fma_f32 v[12:13], v[4:5], v[12:13], v[8:9]
	s_andn2_b64 vcc, exec, s[14:15]
	s_cbranch_vccnz .LBB0_1275
	global_store_dwordx4 v[22:23], v[10:13], off nt
